# attention main loop: separate straight-line loop bodies for leading/trailing halves, rare paths (near tile, bias rebuild, rescale) out of line
# speedup vs baseline: 1.0109x; 1.0060x over previous
.LBB0_270:
	s_waitcnt lgkmcnt(0)
	v_max_f32_e32 v1, v1, v1
	v_max_f32_e32 v0, v0, v0
	v_max_f32_e32 v69, v0, v1
	v_sub_f32_e32 v32, v32, v69
	v_sub_f32_e32 v16, v16, v69
	v_sub_f32_e32 v33, v33, v69
	v_sub_f32_e32 v68, v46, v69
	v_sub_f32_e32 v46, v17, v69
	v_exp_f32_e32 v16, v16
	v_exp_f32_e32 v17, v32
	v_sub_f32_e32 v34, v34, v69
	v_sub_f32_e32 v70, v47, v69
	v_sub_f32_e32 v47, v18, v69
	v_sub_f32_e32 v71, v19, v69
	v_exp_f32_e32 v18, v46
	v_exp_f32_e32 v19, v33
	v_sub_f32_e32 v35, v35, v69
	v_sub_f32_e32 v72, v20, v69
	v_sub_f32_e32 v73, v21, v69
	v_exp_f32_e32 v20, v47
	v_exp_f32_e32 v21, v34
	v_sub_f32_e32 v36, v36, v69
	v_sub_f32_e32 v74, v22, v69
	v_sub_f32_e32 v75, v23, v69
	v_exp_f32_e32 v22, v71
	v_exp_f32_e32 v23, v35
	v_sub_f32_e32 v37, v37, v69
	v_sub_f32_e32 v76, v24, v69
	v_sub_f32_e32 v77, v25, v69
	v_sub_f32_e32 v78, v26, v69
	v_sub_f32_e32 v79, v27, v69
	v_pk_add_f32 v[24:25], v[16:17], 0 op_sel_hi:[1,0]
	v_exp_f32_e32 v26, v72
	v_exp_f32_e32 v27, v36
	v_sub_f32_e32 v38, v38, v69
	v_sub_f32_e32 v80, v28, v69
	v_sub_f32_e32 v81, v29, v69
	v_pk_add_f32 v[24:25], v[18:19], v[24:25]
	v_exp_f32_e32 v28, v73
	v_exp_f32_e32 v29, v37
	v_sub_f32_e32 v39, v39, v69
	v_sub_f32_e32 v82, v30, v69
	v_sub_f32_e32 v83, v31, v69
	v_pk_add_f32 v[24:25], v[20:21], v[24:25]
	v_exp_f32_e32 v30, v74
	v_exp_f32_e32 v31, v38
	v_sub_f32_e32 v40, v40, v69
	v_pk_add_f32 v[24:25], v[22:23], v[24:25]
	v_exp_f32_e32 v32, v75
	v_exp_f32_e32 v33, v39
	v_sub_f32_e32 v41, v41, v69
	v_exp_f32_e32 v34, v76
	v_exp_f32_e32 v35, v40
	v_pk_add_f32 v[24:25], v[26:27], v[24:25]
	v_sub_f32_e32 v42, v42, v69
	v_exp_f32_e32 v36, v77
	v_exp_f32_e32 v37, v41
	v_pk_add_f32 v[24:25], v[28:29], v[24:25]
	v_sub_f32_e32 v43, v43, v69
	v_exp_f32_e32 v38, v78
	v_exp_f32_e32 v39, v42
	v_pk_add_f32 v[24:25], v[30:31], v[24:25]
	v_sub_f32_e32 v44, v44, v69
	v_exp_f32_e32 v40, v79
	v_exp_f32_e32 v41, v43
	v_pk_add_f32 v[24:25], v[32:33], v[24:25]
	v_sub_f32_e32 v45, v45, v69
	v_exp_f32_e32 v42, v80
	v_exp_f32_e32 v43, v44
	v_pk_add_f32 v[24:25], v[34:35], v[24:25]
	v_exp_f32_e32 v44, v81
	v_exp_f32_e32 v45, v45
	v_pk_add_f32 v[24:25], v[36:37], v[24:25]
	v_exp_f32_e32 v46, v82
	v_exp_f32_e32 v47, v68
	v_pk_add_f32 v[24:25], v[38:39], v[24:25]
	v_exp_f32_e32 v82, v83
	v_exp_f32_e32 v83, v70
	v_pk_add_f32 v[24:25], v[40:41], v[24:25]
	s_add_i32 s64, s64, 1
	v_exp_f32_e64 v0, -v69
	v_pk_add_f32 v[24:25], v[42:43], v[24:25]
	s_cmp_lt_u32 s64, s37
	v_pk_add_f32 v[24:25], v[44:45], v[24:25]
	s_cselect_b32 s12, s96, 0
	v_pk_add_f32 v[24:25], v[46:47], v[24:25]
	s_add_i32 s27, s12, s27
	v_pk_add_f32 v[24:25], v[82:83], v[24:25]
	s_ashr_i32 s12, s27, 6
	s_bfe_u32 s54, s27, 0x20004
	v_mul_f32_e32 v0, 0, v0
	v_pk_add_f32 v[24:25], v[24:25], v[24:25] op_sel:[0,1] op_sel_hi:[1,0]
	s_lshl_b32 s36, s12, 4
	s_lshl_b32 s53, s54, 1
	v_mov_b32_e32 v68, v0
	v_mov_b32_e32 v25, v189
	s_or_b32 s53, s53, s36
	s_lshl_b32 s36, s63, 7
	s_and_b32 s55, s58, 0x780
	v_pk_add_f32 v[206:207], v[68:69], v[24:25]
	v_cvt_pk_bf16_f32 v68, v16, v18
	s_and_b32 s36, s36, 0x1800
	v_add_lshl_u32 v16, v158, s55, 2
	v_sub_u32_e32 v16, s36, v16
	v_cvt_pk_bf16_f32 v69, v20, v22
	v_cvt_pk_bf16_f32 v70, v26, v28
	v_cvt_pk_bf16_f32 v71, v30, v32
	v_cvt_pk_bf16_f32 v76, v17, v19
	v_cvt_pk_bf16_f32 v77, v21, v23
	v_cvt_pk_bf16_f32 v78, v27, v29
	v_cvt_pk_bf16_f32 v79, v31, v33
	v_add_u32_e32 v167, v215, v16
	ds_read_b128 v[16:19], v64 offset:20480
	ds_read_b128 v[20:23], v65 offset:20480
	ds_read_b128 v[24:27], v66 offset:20480
	ds_read_b128 v[28:31], v67 offset:20480
	s_lshl_b32 s54, s54, 7
	s_lshl_b32 s12, s12, 9
	v_mov_b32_e32 v1, v0
	v_mov_b32_e32 v2, v0
	v_mov_b32_e32 v3, v0
	v_mov_b32_e32 v4, v0
	v_mov_b32_e32 v5, v0
	v_mov_b32_e32 v6, v0
	v_mov_b32_e32 v7, v0
	v_mov_b32_e32 v8, v0
	v_mov_b32_e32 v9, v0
	v_mov_b32_e32 v10, v0
	v_mov_b32_e32 v11, v0
	v_mov_b32_e32 v12, v0
	v_mov_b32_e32 v13, v0
	v_mov_b32_e32 v14, v0
	v_mov_b32_e32 v15, v0
	s_mov_b32 s23, 0
	s_sub_i32 s36, s62, s55
	s_or_b32 s12, s54, s12
	v_cvt_pk_bf16_f32 v72, v34, v36
	v_cvt_pk_bf16_f32 v73, v38, v40
	v_cvt_pk_bf16_f32 v74, v42, v44
	v_cvt_pk_bf16_f32 v75, v46, v82
	v_cvt_pk_bf16_f32 v80, v35, v37
	v_cvt_pk_bf16_f32 v81, v39, v41
	v_cvt_pk_bf16_f32 v82, v43, v45
	v_cvt_pk_bf16_f32 v83, v47, v83
	v_mfma_f32_32x32x16_bf16 v[32:47], v[56:59], v[68:71], v[0:15]
	v_mfma_f32_32x32x16_bf16 v[32:47], v[48:51], v[72:75], v[32:47]
	v_mfma_f32_32x32x16_bf16 v[32:47], v[60:63], v[76:79], v[32:47]
	v_mfma_f32_32x32x16_bf16 v[32:47], v[52:55], v[80:83], v[32:47]
	s_add_i32 s54, s33, 0x8000
	s_and_b32 s54, s54, 0x18000
	v_add_u32_e32 v48, s54, v149
	v_add_u32_e32 v49, v48, v157
	ds_read_b128 v[132:135], v49
	ds_read_b128 v[116:119], v49 offset:4096
	v_add_u32_e32 v49, v48, v193
	ds_read_b128 v[136:139], v49
	ds_read_b128 v[120:123], v49 offset:4096
	v_add_u32_e32 v49, v48, v208
	v_add_u32_e32 v48, v48, v209
	ds_read_b128 v[140:143], v49
	ds_read_b128 v[124:127], v49 offset:4096
	ds_read_b128 v[128:131], v48
	ds_read_b128 v[112:115], v48 offset:4096
	ds_read_b128 v[84:87], v64 offset:24576
	ds_read_b128 v[88:91], v65 offset:24576
	ds_read_b128 v[92:95], v66 offset:24576
	ds_read_b128 v[216:219], v67 offset:24576
	s_waitcnt lgkmcnt(0)
	v_mfma_f32_32x32x16_bf16 v[48:63], v[16:19], v[68:71], v[0:15]
	v_mfma_f32_32x32x16_bf16 v[48:63], v[20:23], v[72:75], v[48:63]
	v_mfma_f32_32x32x16_bf16 v[48:63], v[24:27], v[76:79], v[48:63]
	v_mfma_f32_32x32x16_bf16 v[48:63], v[28:31], v[80:83], v[48:63]
	ds_read_b128 v[220:223], v64 offset:28672
	ds_read_b128 v[234:237], v65 offset:28672
	ds_read_b128 v[238:241], v66 offset:28672
	ds_read_b128 v[64:67], v67 offset:28672
	v_mfma_f32_32x32x16_bf16 v[16:31], v[84:87], v[68:71], v[0:15]
	v_mfma_f32_32x32x16_bf16 v[16:31], v[88:91], v[72:75], v[16:31]
	v_mfma_f32_32x32x16_bf16 v[16:31], v[92:95], v[76:79], v[16:31]
	v_mfma_f32_32x32x16_bf16 v[16:31], v[216:219], v[80:83], v[16:31]
	s_waitcnt lgkmcnt(0)
	v_mfma_f32_32x32x16_bf16 v[0:15], v[220:223], v[68:71], v[0:15]
	s_waitcnt lgkmcnt(0)
	s_barrier
	s_add_i32 s65, s33, 0x10000
	s_mov_b32 s33, 0
	v_mfma_f32_32x32x16_bf16 v[0:15], v[234:237], v[72:75], v[0:15]
	v_mfma_f32_32x32x16_bf16 v[0:15], v[238:241], v[76:79], v[0:15]
	v_mfma_f32_32x32x16_bf16 v[0:15], v[64:67], v[80:83], v[0:15]
	s_setprio 0
	s_and_b64 vcc, exec, s[42:43]
	s_cbranch_vccnz .LqT_top
.LqL_top:
	s_cmp_gt_u32 s36, 0xfffffeec
	s_cbranch_scc1 .LqL_near
	s_add_i32 s54, s36, 0x7a
	s_cmpk_lt_i32 s54, 0xff67
	s_cselect_b32 s99, 1, 2
	s_cmp_eq_u32 s99, s98
	s_cbranch_scc0 .LqL_cbbuild
.LqL_cbok:
	v_mfma_f32_32x32x16_bf16 v[64:79], v[132:135], v[108:111], v[168:183]
	s_add_i32 s54, s65, 0xffff8000
	s_and_b32 s54, s54, 0x18000
	v_mfma_f32_32x32x16_bf16 v[80:95], v[116:119], v[108:111], v[168:183]
.LqL_rest:
	v_add_u32_e32 v116, s54, v214
	v_add_u32_e32 v216, v116, v157
	v_add_u32_e32 v218, v116, v208
	v_add_u32_e32 v217, v116, v193
	v_add_u32_e32 v219, v116, v209
	v_mfma_f32_32x32x16_bf16 v[64:79], v[136:139], v[104:107], v[64:79]
	v_mfma_f32_32x32x16_bf16 v[80:95], v[120:123], v[104:107], v[80:95]
	v_mfma_f32_32x32x16_bf16 v[64:79], v[140:143], v[100:103], v[64:79]
	v_mfma_f32_32x32x16_bf16 v[80:95], v[124:127], v[100:103], v[80:95]
	v_mfma_f32_32x32x16_bf16 v[80:95], v[112:115], v[96:99], v[80:95]
	ds_read_b128 v[242:245], v216 offset:16384
	ds_read_b128 v[246:249], v216 offset:20480
	ds_read_b128 v[250:253], v216 offset:24576
	ds_read_b128 v[200:203], v216 offset:28672
	ds_read_b128 v[220:223], v217 offset:16384
	ds_read_b128 v[224:227], v217 offset:20480
	ds_read_b128 v[234:237], v217 offset:24576
	ds_read_b128 v[238:241], v217 offset:28672
	v_mfma_f32_32x32x16_bf16 v[64:79], v[128:131], v[96:99], v[64:79]
	s_nop 11
	v_max_f32_e32 v128, v65, v65
	v_max_f32_e32 v129, v64, v64
	v_max_f32_e32 v128, v129, v128
	v_max3_f32 v129, v66, v67, v81
	v_max3_f32 v128, v128, v80, v82
	v_max3_f32 v128, v128, v83, v68
	v_max3_f32 v129, v129, v70, v71
	v_max3_f32 v128, v128, v69, v84
	v_max3_f32 v129, v129, v86, v87
	v_max3_f32 v128, v128, v85, v72
	v_max3_f32 v129, v129, v74, v75
	v_max3_f32 v128, v128, v73, v88
	v_max3_f32 v129, v129, v90, v91
	v_max3_f32 v128, v128, v89, v76
	v_max3_f32 v129, v129, v78, v79
	v_max3_f32 v128, v128, v77, v92
	v_max3_f32 v129, v129, v94, v95
	v_max3_f32 v128, v128, v93, v129
	v_cmp_lt_f32_e32 vcc, s88, v128
	s_cbranch_vccnz .LqL_rescale
.LqL_g0:
	v_exp_f32_e32 v64, v64
	v_exp_f32_e32 v65, v65
	v_exp_f32_e32 v66, v66
	v_exp_f32_e32 v67, v67
	v_add_f32_e32 v184, v64, v65
	v_exp_f32_e32 v68, v68
	v_exp_f32_e32 v69, v69
	v_cvt_pk_bf16_f32 v64, v64, v65
	v_add_f32_e32 v185, v66, v67
	v_cvt_pk_bf16_f32 v65, v66, v67
	v_exp_f32_e32 v70, v70
	v_exp_f32_e32 v71, v71
	v_add_f32_e32 v186, v68, v69
	v_cvt_pk_bf16_f32 v66, v68, v69
	v_add_f32_e32 v184, v184, v185
	v_add_f32_e32 v187, v70, v71
	v_cvt_pk_bf16_f32 v67, v70, v71
	v_add_f32_e32 v186, v186, v187
	v_add_f32_e32 v184, v184, v186
	v_add_f32_e32 v206, v206, v184
	s_waitcnt vmcnt(8) lgkmcnt(0)
	s_barrier
	s_add_i32 s54, s33, 1
	s_setprio 1
	s_cmp_eq_u32 s54, 1
	s_cbranch_scc1 .LqL_full
	s_cmp_eq_u32 s54, 29
	s_cbranch_scc1 .LqL_full
	s_add_u32 s70, s70, 0x2000
	s_addc_u32 s71, s71, 0
	s_add_u32 s66, s66, 0x80
	s_addc_u32 s67, s67, 0
.LqL_ldsb:
	s_add_i32 s33, s65, 0x10000
	s_and_b32 s33, s33, 0x18000
	s_add_i32 s33, s57, s33
	v_lshlrev_b32_e32 v198, 1, v150
	v_mfma_f32_32x32x16_bf16 v[32:47], v[242:245], v[64:67], v[32:47]
	v_exp_f32_e32 v72, v72
	v_exp_f32_e32 v73, v73
	v_exp_f32_e32 v74, v74
	v_exp_f32_e32 v75, v75
	v_add_f32_e32 v184, v72, v73
	s_and_b32 s100, s65, 0x18000
	v_add_u32_e32 v194, s100, v149
	v_add_u32_e32 v195, v194, v157
	v_add_u32_e32 v196, v194, v193
	s_mov_b32 m0, s33
	s_nop 0
	global_load_lds_dwordx4 v188, s[70:71]
	v_mfma_f32_32x32x16_bf16 v[48:63], v[246:249], v[64:67], v[48:63]
	v_exp_f32_e32 v76, v76
	v_exp_f32_e32 v77, v77
	v_cvt_pk_bf16_f32 v68, v72, v73
	v_add_f32_e32 v185, v74, v75
	v_cvt_pk_bf16_f32 v69, v74, v75
	v_add_u32_e32 v197, v194, v208
	v_add_u32_e32 v194, v194, v209
	ds_read_b128 v[132:135], v195
	ds_read_b128 v[116:119], v195 offset:4096
	v_mfma_f32_32x32x16_bf16 v[16:31], v[250:253], v[64:67], v[16:31]
	v_exp_f32_e32 v78, v78
	v_exp_f32_e32 v79, v79
	v_add_f32_e32 v186, v76, v77
	v_cvt_pk_bf16_f32 v70, v76, v77
	v_add_f32_e32 v184, v184, v185
	ds_read_b128 v[136:139], v196
	ds_read_b128 v[120:123], v196 offset:4096
	ds_read_b128 v[140:143], v197
	ds_read_b128 v[124:127], v197 offset:4096
	s_add_u32 s100, s70, 0x40000
	s_addc_u32 s101, s71, 0
	s_add_i32 m0, s33, 0x2000
	s_nop 0
	global_load_lds_dwordx4 v188, s[100:101]
	v_mfma_f32_32x32x16_bf16 v[0:15], v[200:203], v[64:67], v[0:15]
	v_add_f32_e32 v187, v78, v79
	v_cvt_pk_bf16_f32 v71, v78, v79
	v_add_f32_e32 v186, v186, v187
	v_add_f32_e32 v184, v184, v186
	v_add_f32_e32 v206, v206, v184
	ds_read_b128 v[128:131], v194
	ds_read_b128 v[112:115], v194 offset:4096
	ds_read_b128 v[242:245], v218 offset:16384
	ds_read_b128 v[246:249], v218 offset:20480
	ds_read_b128 v[250:253], v218 offset:24576
	ds_read_b128 v[200:203], v218 offset:28672
	v_mfma_f32_32x32x16_bf16 v[32:47], v[220:223], v[68:71], v[32:47]
	v_exp_f32_e32 v80, v80
	v_exp_f32_e32 v81, v81
	v_exp_f32_e32 v82, v82
	v_exp_f32_e32 v83, v83
	v_add_f32_e32 v184, v80, v81
	s_add_i32 m0, s33, 0x4000
	s_nop 0
	global_load_lds_dwordx4 v198, s[66:67]
	v_mfma_f32_32x32x16_bf16 v[48:63], v[224:227], v[68:71], v[48:63]
	v_exp_f32_e32 v84, v84
	v_exp_f32_e32 v85, v85
	v_cvt_pk_bf16_f32 v72, v80, v81
	v_add_f32_e32 v185, v82, v83
	v_cvt_pk_bf16_f32 v73, v82, v83
	v_mfma_f32_32x32x16_bf16 v[16:31], v[234:237], v[68:71], v[16:31]
	v_exp_f32_e32 v86, v86
	v_exp_f32_e32 v87, v87
	v_add_f32_e32 v186, v84, v85
	v_cvt_pk_bf16_f32 v74, v84, v85
	v_add_f32_e32 v184, v184, v185
	s_add_u32 s100, s66, 0x40000
	s_addc_u32 s101, s67, 0
	s_add_i32 m0, s33, 0x6000
	s_nop 0
	global_load_lds_dwordx4 v198, s[100:101]
	v_mfma_f32_32x32x16_bf16 v[0:15], v[238:241], v[68:71], v[0:15]
	v_add_f32_e32 v187, v86, v87
	v_cvt_pk_bf16_f32 v75, v86, v87
	v_add_f32_e32 v186, v186, v187
	v_add_f32_e32 v184, v184, v186
	v_add_f32_e32 v206, v206, v184
	ds_read_b128 v[220:223], v219 offset:16384
	ds_read_b128 v[224:227], v219 offset:20480
	ds_read_b128 v[234:237], v219 offset:24576
	ds_read_b128 v[238:241], v219 offset:28672
	s_waitcnt lgkmcnt(4)
	v_mfma_f32_32x32x16_bf16 v[32:47], v[242:245], v[72:75], v[32:47]
	v_exp_f32_e32 v88, v88
	v_exp_f32_e32 v89, v89
	v_exp_f32_e32 v90, v90
	v_exp_f32_e32 v91, v91
	v_add_f32_e32 v184, v88, v89
	s_add_u32 s100, s70, 0x1000
	s_addc_u32 s101, s71, 0
	s_add_i32 m0, s33, 0x1000
	s_nop 0
	global_load_lds_dwordx4 v188, s[100:101]
	v_mfma_f32_32x32x16_bf16 v[48:63], v[246:249], v[72:75], v[48:63]
	v_exp_f32_e32 v92, v92
	v_exp_f32_e32 v93, v93
	v_cvt_pk_bf16_f32 v76, v88, v89
	v_add_f32_e32 v185, v90, v91
	v_cvt_pk_bf16_f32 v77, v90, v91
	v_mfma_f32_32x32x16_bf16 v[16:31], v[250:253], v[72:75], v[16:31]
	v_exp_f32_e32 v94, v94
	v_exp_f32_e32 v95, v95
	v_add_f32_e32 v186, v92, v93
	v_cvt_pk_bf16_f32 v78, v92, v93
	v_add_f32_e32 v184, v184, v185
	s_add_u32 s100, s70, 0x41000
	s_addc_u32 s101, s71, 0
	s_add_i32 m0, s33, 0x3000
	s_nop 0
	global_load_lds_dwordx4 v188, s[100:101]
	v_mfma_f32_32x32x16_bf16 v[0:15], v[200:203], v[72:75], v[0:15]
	v_add_f32_e32 v187, v94, v95
	v_cvt_pk_bf16_f32 v79, v94, v95
	v_add_f32_e32 v186, v186, v187
	v_add_f32_e32 v184, v184, v186
	v_add_f32_e32 v206, v206, v184
	s_waitcnt lgkmcnt(0)
	v_mfma_f32_32x32x16_bf16 v[32:47], v[220:223], v[76:79], v[32:47]
	s_add_u32 s100, s66, 0x20000
	s_addc_u32 s101, s67, 0
	s_add_i32 m0, s33, 0x5000
	s_nop 0
	global_load_lds_dwordx4 v198, s[100:101]
	v_mfma_f32_32x32x16_bf16 v[48:63], v[224:227], v[76:79], v[48:63]
	s_add_u32 s100, s66, 0x60000
	s_addc_u32 s101, s67, 0
	s_add_i32 m0, s33, 0x7000
	s_nop 0
	global_load_lds_dwordx4 v198, s[100:101]
	s_waitcnt lgkmcnt(0)
	s_barrier
	s_add_i32 s65, s65, 0x8000
	s_addk_i32 s23, 0x100
	s_add_i32 s36, s36, 64
	s_mov_b32 s33, s54
	s_setprio 0
	s_cmpk_eq_i32 s23, 0x1e00
	v_mfma_f32_32x32x16_bf16 v[16:31], v[234:237], v[76:79], v[16:31]
	v_mfma_f32_32x32x16_bf16 v[0:15], v[238:241], v[76:79], v[0:15]
	s_cbranch_scc0 .LqL_top
	s_branch .LBB0_284
.LqL_near:
	v_add_u32_e32 v78, s23, v167
	v_add_u32_e32 v64, 0x204fc, v78
	v_add_u32_e32 v66, 0x2057c, v78
	v_add_u32_e32 v67, 0x20504, v78
	v_add_u32_e32 v68, 0x20584, v78
	ds_read2_b32 v[64:65], v64 offset1:1
	ds_read2_b32 v[80:81], v66 offset1:1
	ds_read2_b32 v[66:67], v67 offset1:1
	ds_read2_b32 v[82:83], v68 offset1:1
	v_add_u32_e32 v68, 0x2051c, v78
	v_add_u32_e32 v70, 0x2059c, v78
	v_add_u32_e32 v71, 0x20524, v78
	v_add_u32_e32 v72, 0x205a4, v78
	ds_read2_b32 v[68:69], v68 offset1:1
	ds_read2_b32 v[84:85], v70 offset1:1
	ds_read2_b32 v[70:71], v71 offset1:1
	ds_read2_b32 v[86:87], v72 offset1:1
	v_add_u32_e32 v72, 0x2053c, v78
	v_add_u32_e32 v74, 0x205bc, v78
	v_add_u32_e32 v75, 0x20544, v78
	v_add_u32_e32 v76, 0x205c4, v78
	ds_read2_b32 v[72:73], v72 offset1:1
	ds_read2_b32 v[88:89], v74 offset1:1
	ds_read2_b32 v[74:75], v75 offset1:1
	ds_read2_b32 v[90:91], v76 offset1:1
	v_add_u32_e32 v76, 0x2055c, v78
	v_add_u32_e32 v92, 0x205dc, v78
	v_add_u32_e32 v79, 0x20564, v78
	v_add_u32_e32 v93, 0x205e4, v78
	ds_read2_b32 v[76:77], v76 offset1:1
	ds_read2_b32 v[78:79], v79 offset1:1
	ds_read2_b32 v[94:95], v93 offset1:1
	ds_read2_b32 v[92:93], v92 offset1:1
	s_waitcnt lgkmcnt(0)
	v_sub_f32_e32 v65, v65, v207
	v_sub_f32_e32 v66, v66, v207
	v_sub_f32_e32 v67, v67, v207
	v_sub_f32_e32 v68, v68, v207
	v_sub_f32_e32 v69, v69, v207
	v_sub_f32_e32 v70, v70, v207
	v_sub_f32_e32 v71, v71, v207
	v_sub_f32_e32 v72, v72, v207
	v_sub_f32_e32 v73, v73, v207
	v_sub_f32_e32 v74, v74, v207
	v_sub_f32_e32 v75, v75, v207
	v_sub_f32_e32 v76, v76, v207
	v_sub_f32_e32 v77, v77, v207
	v_sub_f32_e32 v78, v78, v207
	v_sub_f32_e32 v79, v79, v207
	v_sub_f32_e32 v64, v64, v207
	v_sub_f32_e32 v81, v81, v207
	v_sub_f32_e32 v82, v82, v207
	v_sub_f32_e32 v83, v83, v207
	v_sub_f32_e32 v84, v84, v207
	v_sub_f32_e32 v85, v85, v207
	v_sub_f32_e32 v86, v86, v207
	v_sub_f32_e32 v87, v87, v207
	v_sub_f32_e32 v88, v88, v207
	v_sub_f32_e32 v89, v89, v207
	v_sub_f32_e32 v90, v90, v207
	v_sub_f32_e32 v91, v91, v207
	v_sub_f32_e32 v92, v92, v207
	v_sub_f32_e32 v93, v93, v207
	v_sub_f32_e32 v94, v94, v207
	v_sub_f32_e32 v95, v95, v207
	v_sub_f32_e32 v80, v80, v207
	s_nop 1
	v_mfma_f32_32x32x16_bf16 v[64:79], v[132:135], v[108:111], v[64:79]
	s_add_i32 s54, s65, 0xffff8000
	s_and_b32 s54, s54, 0x18000
	v_mfma_f32_32x32x16_bf16 v[80:95], v[116:119], v[108:111], v[80:95]
	s_branch .LqL_rest
.LqL_cbbuild:
	s_cmp_eq_u32 s99, 1
	s_cselect_b64 vcc, -1, 0
	s_mov_b32 s98, s99
	v_cndmask_b32_e32 v168, v152, v145, vcc
	v_sub_f32_e32 v168, v168, v207
	v_mov_b32_e32 v169, v168
	v_mov_b32_e32 v170, v168
	v_mov_b32_e32 v171, v168
	v_mov_b32_e32 v172, v168
	v_mov_b32_e32 v173, v168
	v_mov_b32_e32 v174, v168
	v_mov_b32_e32 v175, v168
	v_mov_b32_e32 v176, v168
	v_mov_b32_e32 v177, v168
	v_mov_b32_e32 v178, v168
	v_mov_b32_e32 v179, v168
	v_mov_b32_e32 v180, v168
	v_mov_b32_e32 v181, v168
	v_mov_b32_e32 v182, v168
	v_mov_b32_e32 v183, v168
	s_nop 1
	s_branch .LqL_cbok
.LqL_rescale:
	s_mov_b32 s98, 0
	ds_bpermute_b32 v129, v210, v128
	s_waitcnt lgkmcnt(0)
	v_max_f32_e32 v129, v129, v129
	v_max_f32_e32 v128, v128, v129
	v_cmp_lt_f32_e32 vcc, s88, v128
	s_nop 0
	s_nop 0
	v_cndmask_b32_e32 v128, 0, v128, vcc
	v_exp_f32_e64 v130, -v128
	v_pk_add_f32 v[64:65], v[64:65], v[128:129] op_sel_hi:[1,0] neg_lo:[0,1] neg_hi:[0,1]
	v_pk_add_f32 v[80:81], v[80:81], v[128:129] op_sel_hi:[1,0] neg_lo:[0,1] neg_hi:[0,1]
	v_pk_add_f32 v[66:67], v[66:67], v[128:129] op_sel_hi:[1,0] neg_lo:[0,1] neg_hi:[0,1]
	v_pk_mul_f32 v[46:47], v[46:47], v[130:131] op_sel_hi:[1,0]
	v_pk_mul_f32 v[44:45], v[44:45], v[130:131] op_sel_hi:[1,0]
	v_pk_mul_f32 v[42:43], v[42:43], v[130:131] op_sel_hi:[1,0]
	v_pk_mul_f32 v[40:41], v[40:41], v[130:131] op_sel_hi:[1,0]
	v_pk_mul_f32 v[38:39], v[38:39], v[130:131] op_sel_hi:[1,0]
	v_pk_mul_f32 v[36:37], v[36:37], v[130:131] op_sel_hi:[1,0]
	v_pk_mul_f32 v[34:35], v[34:35], v[130:131] op_sel_hi:[1,0]
	v_pk_mul_f32 v[32:33], v[32:33], v[130:131] op_sel_hi:[1,0]
	v_pk_mul_f32 v[62:63], v[62:63], v[130:131] op_sel_hi:[1,0]
	v_pk_mul_f32 v[60:61], v[60:61], v[130:131] op_sel_hi:[1,0]
	v_pk_mul_f32 v[58:59], v[58:59], v[130:131] op_sel_hi:[1,0]
	v_pk_mul_f32 v[56:57], v[56:57], v[130:131] op_sel_hi:[1,0]
	v_pk_mul_f32 v[54:55], v[54:55], v[130:131] op_sel_hi:[1,0]
	v_pk_mul_f32 v[52:53], v[52:53], v[130:131] op_sel_hi:[1,0]
	v_pk_mul_f32 v[50:51], v[50:51], v[130:131] op_sel_hi:[1,0]
	v_pk_mul_f32 v[48:49], v[48:49], v[130:131] op_sel_hi:[1,0]
	v_pk_mul_f32 v[30:31], v[30:31], v[130:131] op_sel_hi:[1,0]
	v_pk_mul_f32 v[28:29], v[28:29], v[130:131] op_sel_hi:[1,0]
	v_pk_mul_f32 v[26:27], v[26:27], v[130:131] op_sel_hi:[1,0]
	v_pk_mul_f32 v[24:25], v[24:25], v[130:131] op_sel_hi:[1,0]
	v_pk_mul_f32 v[22:23], v[22:23], v[130:131] op_sel_hi:[1,0]
	v_pk_mul_f32 v[20:21], v[20:21], v[130:131] op_sel_hi:[1,0]
	v_pk_mul_f32 v[18:19], v[18:19], v[130:131] op_sel_hi:[1,0]
	v_pk_mul_f32 v[16:17], v[16:17], v[130:131] op_sel_hi:[1,0]
	v_pk_mul_f32 v[14:15], v[14:15], v[130:131] op_sel_hi:[1,0]
	v_pk_mul_f32 v[12:13], v[12:13], v[130:131] op_sel_hi:[1,0]
	v_pk_mul_f32 v[10:11], v[10:11], v[130:131] op_sel_hi:[1,0]
	v_pk_mul_f32 v[8:9], v[8:9], v[130:131] op_sel_hi:[1,0]
	v_pk_mul_f32 v[6:7], v[6:7], v[130:131] op_sel_hi:[1,0]
	v_pk_mul_f32 v[4:5], v[4:5], v[130:131] op_sel_hi:[1,0]
	v_pk_mul_f32 v[2:3], v[2:3], v[130:131] op_sel_hi:[1,0]
	v_pk_mul_f32 v[0:1], v[0:1], v[130:131] op_sel_hi:[1,0]
	v_mov_b32_e32 v131, v128
	v_pk_add_f32 v[82:83], v[82:83], v[128:129] op_sel_hi:[1,0] neg_lo:[0,1] neg_hi:[0,1]
	v_pk_add_f32 v[68:69], v[68:69], v[128:129] op_sel_hi:[1,0] neg_lo:[0,1] neg_hi:[0,1]
	v_pk_add_f32 v[84:85], v[84:85], v[128:129] op_sel_hi:[1,0] neg_lo:[0,1] neg_hi:[0,1]
	v_pk_add_f32 v[70:71], v[70:71], v[128:129] op_sel_hi:[1,0] neg_lo:[0,1] neg_hi:[0,1]
	v_pk_add_f32 v[86:87], v[86:87], v[128:129] op_sel_hi:[1,0] neg_lo:[0,1] neg_hi:[0,1]
	v_pk_add_f32 v[72:73], v[72:73], v[128:129] op_sel_hi:[1,0] neg_lo:[0,1] neg_hi:[0,1]
	v_pk_add_f32 v[88:89], v[88:89], v[128:129] op_sel_hi:[1,0] neg_lo:[0,1] neg_hi:[0,1]
	v_pk_add_f32 v[74:75], v[74:75], v[128:129] op_sel_hi:[1,0] neg_lo:[0,1] neg_hi:[0,1]
	v_pk_add_f32 v[90:91], v[90:91], v[128:129] op_sel_hi:[1,0] neg_lo:[0,1] neg_hi:[0,1]
	v_pk_add_f32 v[76:77], v[76:77], v[128:129] op_sel_hi:[1,0] neg_lo:[0,1] neg_hi:[0,1]
	v_pk_add_f32 v[92:93], v[92:93], v[128:129] op_sel_hi:[1,0] neg_lo:[0,1] neg_hi:[0,1]
	v_pk_add_f32 v[78:79], v[78:79], v[128:129] op_sel_hi:[1,0] neg_lo:[0,1] neg_hi:[0,1]
	v_pk_add_f32 v[94:95], v[94:95], v[128:129] op_sel_hi:[1,0] neg_lo:[0,1] neg_hi:[0,1]
	v_pk_add_f32 v[128:129], v[206:207], v[130:131]
	v_pk_mul_f32 v[206:207], v[206:207], v[130:131]
	s_nop 0
	v_mov_b32_e32 v207, v129
	s_branch .LqL_g0
.LqL_full:
	s_cmp_lt_u32 s54, 29
	s_cselect_b32 s67, s13, s53
	s_cselect_b32 s55, 3, 0xffffffe3
	s_cselect_b32 s66, s22, s12
	s_or_b32 s70, s67, 8
	s_add_i32 s33, s55, s33
	s_ashr_i32 s71, s70, 31
	s_add_i32 s68, s33, 1
	s_lshl_b64 s[70:71], s[70:71], 18
	s_add_u32 s33, s8, s70
	s_addc_u32 s55, s9, s71
	s_ashr_i32 s69, s68, 31
	s_lshl_b64 s[70:71], s[68:69], 13
	s_add_u32 s70, s33, s70
	s_addc_u32 s71, s55, s71
	s_ashr_i32 s67, s66, 31
	s_lshl_b64 s[66:67], s[66:67], 12
	s_add_u32 s33, s10, s66
	s_addc_u32 s55, s11, s67
	s_lshl_b32 s66, s68, 6
	s_ashr_i32 s67, s66, 31
	s_lshl_b64 s[66:67], s[66:67], 1
	s_add_u32 s66, s33, s66
	s_addc_u32 s67, s55, s67
	s_branch .LqL_ldsb

.LqT_g0:
	v_exp_f32_e32 v64, v64
	v_exp_f32_e32 v65, v65
	v_exp_f32_e32 v66, v66
	v_exp_f32_e32 v67, v67
	v_add_f32_e32 v184, v64, v65
	v_exp_f32_e32 v68, v68
	v_exp_f32_e32 v69, v69
	v_cvt_pk_bf16_f32 v64, v64, v65
	v_add_f32_e32 v185, v66, v67
	v_cvt_pk_bf16_f32 v65, v66, v67
	v_exp_f32_e32 v70, v70
	v_exp_f32_e32 v71, v71
	v_add_f32_e32 v186, v68, v69
	v_cvt_pk_bf16_f32 v66, v68, v69
	v_add_f32_e32 v184, v184, v185
	v_add_f32_e32 v187, v70, v71
	v_cvt_pk_bf16_f32 v67, v70, v71
	v_add_f32_e32 v186, v186, v187
	v_add_f32_e32 v184, v184, v186
	v_add_f32_e32 v206, v206, v184
	s_waitcnt vmcnt(0) lgkmcnt(0)
	s_barrier
	s_add_i32 s54, s33, 1
	s_setprio 1
	v_mfma_f32_32x32x16_bf16 v[32:47], v[242:245], v[64:67], v[32:47]
	v_exp_f32_e32 v72, v72
	v_exp_f32_e32 v73, v73
	v_exp_f32_e32 v74, v74
	v_exp_f32_e32 v75, v75
	v_add_f32_e32 v184, v72, v73
	s_and_b32 s100, s65, 0x18000
	v_add_u32_e32 v194, s100, v149
	v_add_u32_e32 v195, v194, v157
	v_add_u32_e32 v196, v194, v193
	v_mfma_f32_32x32x16_bf16 v[48:63], v[246:249], v[64:67], v[48:63]
	v_exp_f32_e32 v76, v76
	v_exp_f32_e32 v77, v77
	v_cvt_pk_bf16_f32 v68, v72, v73
	v_add_f32_e32 v185, v74, v75
	v_cvt_pk_bf16_f32 v69, v74, v75
	v_add_u32_e32 v197, v194, v208
	v_add_u32_e32 v194, v194, v209
	ds_read_b128 v[132:135], v195
	ds_read_b128 v[116:119], v195 offset:4096
	v_mfma_f32_32x32x16_bf16 v[16:31], v[250:253], v[64:67], v[16:31]
	v_exp_f32_e32 v78, v78
	v_exp_f32_e32 v79, v79
	v_add_f32_e32 v186, v76, v77
	v_cvt_pk_bf16_f32 v70, v76, v77
	v_add_f32_e32 v184, v184, v185
	ds_read_b128 v[136:139], v196
	ds_read_b128 v[120:123], v196 offset:4096
	ds_read_b128 v[140:143], v197
	ds_read_b128 v[124:127], v197 offset:4096
	v_mfma_f32_32x32x16_bf16 v[0:15], v[200:203], v[64:67], v[0:15]
	v_add_f32_e32 v187, v78, v79
	v_cvt_pk_bf16_f32 v71, v78, v79
	v_add_f32_e32 v186, v186, v187
	v_add_f32_e32 v184, v184, v186
	v_add_f32_e32 v206, v206, v184
	ds_read_b128 v[128:131], v194
	ds_read_b128 v[112:115], v194 offset:4096
	ds_read_b128 v[242:245], v218 offset:16384
	ds_read_b128 v[246:249], v218 offset:20480
	ds_read_b128 v[250:253], v218 offset:24576
	ds_read_b128 v[200:203], v218 offset:28672
	v_mfma_f32_32x32x16_bf16 v[32:47], v[220:223], v[68:71], v[32:47]
	v_exp_f32_e32 v80, v80
	v_exp_f32_e32 v81, v81
	v_exp_f32_e32 v82, v82
	v_exp_f32_e32 v83, v83
	v_add_f32_e32 v184, v80, v81
	v_mfma_f32_32x32x16_bf16 v[48:63], v[224:227], v[68:71], v[48:63]
	v_exp_f32_e32 v84, v84
	v_exp_f32_e32 v85, v85
	v_cvt_pk_bf16_f32 v72, v80, v81
	v_add_f32_e32 v185, v82, v83
	v_cvt_pk_bf16_f32 v73, v82, v83
	v_mfma_f32_32x32x16_bf16 v[16:31], v[234:237], v[68:71], v[16:31]
	v_exp_f32_e32 v86, v86
	v_exp_f32_e32 v87, v87
	v_add_f32_e32 v186, v84, v85
	v_cvt_pk_bf16_f32 v74, v84, v85
	v_add_f32_e32 v184, v184, v185
	v_mfma_f32_32x32x16_bf16 v[0:15], v[238:241], v[68:71], v[0:15]
	v_add_f32_e32 v187, v86, v87
	v_cvt_pk_bf16_f32 v75, v86, v87
	v_add_f32_e32 v186, v186, v187
	v_add_f32_e32 v184, v184, v186
	v_add_f32_e32 v206, v206, v184
	ds_read_b128 v[220:223], v219 offset:16384
	ds_read_b128 v[224:227], v219 offset:20480
	ds_read_b128 v[234:237], v219 offset:24576
	ds_read_b128 v[238:241], v219 offset:28672
	s_waitcnt lgkmcnt(4)
	v_mfma_f32_32x32x16_bf16 v[32:47], v[242:245], v[72:75], v[32:47]
	v_exp_f32_e32 v88, v88
	v_exp_f32_e32 v89, v89
	v_exp_f32_e32 v90, v90
	v_exp_f32_e32 v91, v91
	v_add_f32_e32 v184, v88, v89
	v_mfma_f32_32x32x16_bf16 v[48:63], v[246:249], v[72:75], v[48:63]
	v_exp_f32_e32 v92, v92
	v_exp_f32_e32 v93, v93
	v_cvt_pk_bf16_f32 v76, v88, v89
	v_add_f32_e32 v185, v90, v91
	v_cvt_pk_bf16_f32 v77, v90, v91
	v_mfma_f32_32x32x16_bf16 v[16:31], v[250:253], v[72:75], v[16:31]
	v_exp_f32_e32 v94, v94
	v_exp_f32_e32 v95, v95
	v_add_f32_e32 v186, v92, v93
	v_cvt_pk_bf16_f32 v78, v92, v93
	v_add_f32_e32 v184, v184, v185
	v_mfma_f32_32x32x16_bf16 v[0:15], v[200:203], v[72:75], v[0:15]
	v_add_f32_e32 v187, v94, v95
	v_cvt_pk_bf16_f32 v79, v94, v95
	v_add_f32_e32 v186, v186, v187
	v_add_f32_e32 v184, v184, v186
	v_add_f32_e32 v206, v206, v184
	s_waitcnt lgkmcnt(0)
	v_mfma_f32_32x32x16_bf16 v[32:47], v[220:223], v[76:79], v[32:47]
	v_mfma_f32_32x32x16_bf16 v[48:63], v[224:227], v[76:79], v[48:63]
	s_waitcnt lgkmcnt(0)
	s_barrier
	s_add_i32 s65, s65, 0x8000
	s_addk_i32 s23, 0x100
	s_add_i32 s36, s36, 64
	s_mov_b32 s33, s54
	s_setprio 0
	s_cmpk_eq_i32 s23, 0x1e00
	v_mfma_f32_32x32x16_bf16 v[16:31], v[234:237], v[76:79], v[16:31]
	v_mfma_f32_32x32x16_bf16 v[0:15], v[238:241], v[76:79], v[0:15]
	s_cbranch_scc0 .LqT_top
	s_branch .LBB0_284
